# diff-attention tile loop: K/V LDS-DMA source addresses kept as loop-carried pointers (4 adds in the loop tail) instead of 6 64-bit VALU adds right after the barrier
# baseline (speedup 1.0000x reference)
; __device__ __forceinline__ int tid_opq() { int t = threadIdx.x; asm volatile("" : "+v"(t)); return t; }
; #define LAS __attribute__((address_space(3)))
; #define ATT_GLOAD(kt) do { _Pragma("unroll") for (int i = 0; i < NCH; ++i) { const size_t go = goff + (size_t)((kt) * 64 + i * (512 / CPR)) * kvpitch; \
;         kreg[i] = *(const u32x4*)(Kp + go); vreg[i] = *(const u32x4*)(Vp + go); } } while (0)
; template <bool DIFF> ...
;     ...
;     const int tid = tid_opq(), wid = __builtin_amdgcn_readfirstlane(tid >> 6), lane = tid & 63, c = wid >> 2, qr = (wid & 3) * 32, l32 = lane & 31, hi = lane >> 5;
;     constexpr int QSTR = 528, QOFF = STAGE;
;     bf16x8 qf[DIFF ? NKS : 1];
;     if (DIFF) { const bf16_t* qrow = Qp + (size_t)(qr + l32) * qpitch + c * 64 + hi * 8;
; #pragma unroll
;       for (int ks = 0; ks < (DIFF ? NKS : 1); ++ks) qf[ks] = *(const bf16x8*)(qrow + ks * 16); }
;     f32x16 o[4];
; #pragma unroll
;     for (int i = 0; i < 4; ++i)
; #pragma unroll
;         for (int r = 0; r < 16; ++r) o[i][r] = 0.f;
;     float m_run = -INFINITY, l_run = 0.f;
;     u32x4 kreg[NCH], vreg[NCH];
;     const int srow = tid / CPR, sch = tid % CPR;
;     const size_t goff = (size_t)srow * kvpitch + sch * 8;
;     const int loffk = srow * KSTR + sch * 16, loffv = KBY + srow * VSTR + sch * 16;
;     ...
;     constexpr int DSTG = 32768;
;     const int dch = (lane & 15) ^ ((((lane >> 4) & 3) << 2) | (wid & 3));
;     ...
;     __syncthreads();
;     if (DIFF) { ATT_DMA(nkt - 1, 0); }
;     else { ATT_GLOAD(0);
; #pragma unroll
;         for (int i = 0; i < 8; ++i) { const int id = tid + 512 * i, row = id >> 5, ch = id & 31;
;             *(LAS u32x4*)(lds + QOFF + row * QSTR + ch * 16) = *(const u32x4*)(Qp + (size_t)row * qpitch + ch * 8); }
;     }
;     const int wrow = qpos0 + qr;
;     f32x16 biasv;
;     { const float beta = DIFF ? sl2 / sc2 : 0.f;
; #pragma unroll
;       for (int r = 0; r < 16; ++r) biasv[r] = beta * (float)((r >> 2) * 8 + (r & 3) + hi * 4 - l32); }
;     int it = 0;
.LBB0_111:
	s_xor_b64 s[30:31], s[0:1], -1
	s_and_b64 s[0:1], s[0:1], exec
	s_cselect_b32 s0, s45, s5
	s_lshl_b32 s25, s0, 7
	s_mul_i32 s0, s0, 0xb0000
	v_mov_b32_e32 v18, v187
	s_add_u32 s0, s16, s0
	s_addc_u32 s1, s17, 0
	v_readfirstlane_b32 s26, v18
	s_ashr_i32 s14, s26, 6
	s_and_b32 s65, s14, 3
	s_lshl_b32 s22, s65, 5
	v_and_b32_e32 v19, 31, v18
	v_or_b32_e32 v183, s22, v19
	v_mov_b64_e32 v[2:3], s[0:1]
	s_movk_i32 s2, 0x1600
	s_ashr_i32 s64, s26, 8
	v_mad_u64_u32 v[2:3], s[0:1], v183, s2, v[2:3]
	s_lshl_b32 s0, s64, 6
	v_bfe_u32 v20, v18, 5, 1
	s_ashr_i32 s1, s0, 31
	v_lshl_add_u64 v[2:3], s[0:1], 1, v[2:3]
	v_lshlrev_b32_e32 v0, 4, v20
	v_lshl_add_u64 v[2:3], v[2:3], 0, v[0:1]
	v_bfe_u32 v21, v18, 4, 2
	global_load_dwordx4 v[114:117], v[2:3], off
	global_load_dwordx4 v[118:121], v[2:3], off offset:32
	global_load_dwordx4 v[122:125], v[2:3], off offset:64
	global_load_dwordx4 v[126:129], v[2:3], off offset:96
	v_and_b32_e32 v0, 15, v18
	v_lshlrev_b32_e32 v2, 2, v21
	s_or_b32 s20, s25, 64
	v_bitop3_b32 v22, v2, v0, s65 bitop3:0x36
	v_or_b32_e32 v6, s20, v21
	s_lshl_b32 s23, s14, 2
	v_lshlrev_b32_e32 v0, 3, v22
	v_add_u32_e32 v2, s23, v6
	s_movk_i32 s3, 0xb00
	v_mad_i64_i32 v[2:3], s[0:1], v2, s3, v[0:1]
	s_lshl_b32 s21, s14, 10
	v_lshl_add_u64 v[2:3], v[2:3], 1, s[16:17]
	s_mov_b64 s[38:39], 0x400
	s_add_i32 s0, s21, 0
	v_lshl_add_u64 v[4:5], v[2:3], 0, s[38:39]
	s_mov_b32 m0, s0
	s_mov_b64 s[36:37], 0x800
	s_barrier
	global_load_lds_dwordx4 v[4:5], off
	v_lshl_add_u64 v[2:3], v[2:3], 0, s[36:37]
	s_add_i32 m0, s0, 0x4000
	s_add_i32 s14, s14, 8
	global_load_lds_dwordx4 v[2:3], off
	v_lshl_add_u32 v2, s14, 2, v6
	v_mad_i64_i32 v[2:3], s[0:1], v2, s3, v[0:1]
	s_lshl_b32 s14, s14, 10
	v_lshl_add_u64 v[2:3], v[2:3], 1, s[16:17]
	s_add_i32 s0, s14, 0
	v_lshl_add_u64 v[4:5], v[2:3], 0, s[38:39]
	s_mov_b32 m0, s0
	v_lshl_add_u64 v[2:3], v[2:3], 0, s[36:37]
	global_load_lds_dwordx4 v[4:5], off
	s_add_i32 m0, s0, 0x4000
	v_lshlrev_b32_e32 v184, 2, v20
	global_load_lds_dwordx4 v[2:3], off
	v_sub_u32_e32 v0, v184, v19
	v_add_u32_e32 v4, 2, v0
	v_add_u32_e32 v5, 3, v0
	v_cvt_f32_i32_e32 v5, v5
	v_cvt_f32_i32_e32 v4, v4
	v_add_u32_e32 v3, 1, v0
	v_add_u32_e32 v6, 8, v0
	v_add_u32_e32 v7, 9, v0
	v_add_u32_e32 v8, 10, v0
	v_add_u32_e32 v9, 11, v0
	v_add_u32_e32 v10, 16, v0
	v_add_u32_e32 v11, 17, v0
	v_add_u32_e32 v12, 18, v0
	v_add_u32_e32 v13, 19, v0
	v_add_u32_e32 v14, 24, v0
	v_add_u32_e32 v15, 25, v0
	v_add_u32_e32 v16, 26, v0
	v_add_u32_e32 v17, 27, v0
	v_cvt_f32_i32_e32 v2, v0
	v_cvt_f32_i32_e32 v3, v3
	v_cvt_f32_i32_e32 v7, v7
	v_cvt_f32_i32_e32 v6, v6
	v_cvt_f32_i32_e32 v9, v9
	v_cvt_f32_i32_e32 v8, v8
	v_cvt_f32_i32_e32 v11, v11
	v_cvt_f32_i32_e32 v10, v10
	v_cvt_f32_i32_e32 v13, v13
	v_cvt_f32_i32_e32 v15, v15
	v_cvt_f32_i32_e32 v17, v17
	v_cvt_f32_i32_e32 v16, v16
	v_cvt_f32_i32_e32 v14, v14
	v_cvt_f32_i32_e32 v12, v12
	v_mov_b32_e32 v163, v162
	v_pk_mul_f32 v[68:69], v[162:163], v[4:5]
	v_bfe_u32 v4, v18, 2, 2
	v_lshlrev_b32_e32 v5, 8, v4
	v_pk_mul_f32 v[80:81], v[162:163], v[16:17]
	v_pk_mul_f32 v[78:79], v[162:163], v[14:15]
	v_pk_mul_f32 v[76:77], v[162:163], v[12:13]
	v_pk_mul_f32 v[74:75], v[162:163], v[10:11]
	v_pk_mul_f32 v[72:73], v[162:163], v[8:9]
	v_pk_mul_f32 v[70:71], v[162:163], v[6:7]
	v_pk_mul_f32 v[66:67], v[164:165], v[2:3]
	v_lshlrev_b32_e32 v3, 2, v18
	v_lshl_or_b32 v163, v20, 10, v5
	v_lshrrev_b32_e32 v5, 3, v18
	s_lshl_b32 s0, s64, 3
	v_and_or_b32 v3, v3, 12, v4
	v_and_b32_e32 v5, 2, v5
	v_bfe_u32 v6, v18, 1, 1
	v_lshlrev_b32_e32 v0, 8, v19
	v_or_b32_e32 v2, s0, v20
	v_bitop3_b32 v7, v5, v20, v6 bitop3:0x36
	v_lshlrev_b32_e32 v199, 6, v4
	v_bitop3_b32 v4, s0, v3, v20 bitop3:0x36
	v_lshlrev_b32_e32 v186, 4, v7
	v_lshlrev_b32_e32 v7, 3, v18
	v_lshl_add_u32 v200, v4, 4, v0
	v_bitop3_b32 v4, v2, v3, 2 bitop3:0x36
	v_and_b32_e32 v197, 8, v7
	v_or_b32_e32 v7, 2, v20
	v_lshl_add_u32 v201, v4, 4, v0
	v_bitop3_b32 v4, v2, v3, 4 bitop3:0x36
	s_add_i32 s23, s23, s25
	v_bitop3_b32 v5, v5, v7, v6 bitop3:0x36
	v_lshl_add_u32 v202, v4, 4, v0
	v_bitop3_b32 v2, v2, v3, 6 bitop3:0x36
	v_or_b32_e32 v4, s23, v21
	v_lshlrev_b32_e32 v198, 4, v5
	v_lshl_add_u32 v203, v2, 4, v0
	v_add_u32_e32 v5, 32, v4
	v_mov_b64_e32 v[2:3], s[18:19]
	v_mad_i64_i32 v[166:167], s[0:1], v5, s2, v[2:3]
	v_mad_i64_i32 v[168:169], s[0:1], v4, s2, v[2:3]
	s_sub_i32 s0, s22, 64
	s_nop 0
	v_or_b32_e32 v2, s0, v19
	v_mov_b32_e32 v50, v1
	v_mov_b32_e32 v51, v1
	v_and_b32_e32 v185, 63, v18
	v_lshlrev_b32_e32 v0, 4, v22
	v_lshl_add_u64 v[236:237], v[168:169], 0, v[0:1]
	v_lshl_add_u64 v[240:241], v[166:167], 0, v[0:1]
	v_lshl_add_u64 v[238:239], v[236:237], 0, s[6:7]
	v_lshl_add_u64 v[242:243], v[240:241], 0, s[6:7]
	v_lshl_add_u64 v[236:237], v[236:237], 0, s[42:43]
	v_lshl_add_u64 v[240:241], v[240:241], 0, s[42:43]
	v_sub_u32_e32 v204, v2, v184
	v_mov_b32_e32 v52, v1
	v_mov_b32_e32 v53, v1
	v_mov_b32_e32 v54, v1
	v_mov_b32_e32 v55, v1
	v_mov_b32_e32 v56, v1
	v_mov_b32_e32 v57, v1
	v_mov_b32_e32 v58, v1
	v_mov_b32_e32 v59, v1
	v_mov_b32_e32 v60, v1
	v_mov_b32_e32 v61, v1
	v_mov_b32_e32 v62, v1
	v_mov_b32_e32 v63, v1
	v_mov_b32_e32 v64, v1
	v_mov_b32_e32 v65, v1
	v_mov_b64_e32 v[34:35], v[50:51]
	v_mov_b64_e32 v[18:19], v[50:51]
	v_mov_b64_e32 v[2:3], v[50:51]
	s_or_b32 s15, s22, s25
	s_mov_b32 s28, 0
	s_sub_i32 s24, 0, s22
	s_mov_b32 s22, 0
	v_xor_b32_e32 v206, 64, v199
	v_xor_b32_e32 v207, 0x80, v199
	v_xor_b32_e32 v208, 0xc0, v199
	v_mov_b32_e32 v209, 0xff800000
	v_mov_b32_e32 v205, 0
	v_mov_b64_e32 v[36:37], v[52:53]
	v_mov_b64_e32 v[38:39], v[54:55]
	v_mov_b64_e32 v[40:41], v[56:57]
	v_mov_b64_e32 v[42:43], v[58:59]
	v_mov_b64_e32 v[44:45], v[60:61]
	v_mov_b64_e32 v[46:47], v[62:63]
	v_mov_b64_e32 v[48:49], v[64:65]
	v_mov_b64_e32 v[20:21], v[52:53]
	v_mov_b64_e32 v[22:23], v[54:55]
	v_mov_b64_e32 v[24:25], v[56:57]
	v_mov_b64_e32 v[26:27], v[58:59]
	v_mov_b64_e32 v[28:29], v[60:61]
	v_mov_b64_e32 v[30:31], v[62:63]
	v_mov_b64_e32 v[32:33], v[64:65]
	v_mov_b64_e32 v[4:5], v[52:53]
	v_mov_b64_e32 v[6:7], v[54:55]
	v_mov_b64_e32 v[8:9], v[56:57]
	v_mov_b64_e32 v[10:11], v[58:59]
	v_mov_b64_e32 v[12:13], v[60:61]
	v_mov_b64_e32 v[14:15], v[62:63]
	v_mov_b64_e32 v[16:17], v[64:65]
	s_waitcnt vmcnt(0)
	s_branch .LBB0_114

; template <bool DIFF> ...
;     ...
;     for (int kt = DIFF ? nkt - 1 : 0; DIFF ? (kt >= 0) : (kt < nkt); kt += DIFF ? -1 : 1, ++it) {
;         if (DIFF) asm volatile("s_waitcnt vmcnt(0)" ::: "memory");
;         __syncthreads();
;         if (DIFF) { if (kt > 0) ATT_DMA(kt - 1, (it + 1) & 1); }
.LBB0_113:
	s_sub_i32 s22, s22, 64
	s_add_i32 s0, s25, s22
	s_add_i32 s28, s28, 0x8000
	v_lshl_add_u64 v[236:237], v[236:237], 0, s[8:9]
	v_lshl_add_u64 v[238:239], v[238:239], 0, s[8:9]
	v_lshl_add_u64 v[240:241], v[240:241], 0, s[8:9]
	v_lshl_add_u64 v[242:243], v[242:243], 0, s[8:9]
	s_cmpk_eq_i32 s0, 0xff80
	v_add_u32_e32 v204, 64, v204
	s_cbranch_scc1 .LBB0_121
.LBB0_114:
	s_waitcnt vmcnt(0)
	s_add_i32 s0, s20, s22
	s_cmp_eq_u32 s0, 0
	s_waitcnt lgkmcnt(0)
	s_barrier
	s_cbranch_scc1 .LBB0_116
	s_andn2_b32 s0, 0x8000, s28
	s_add_i32 s0, s0, 0
	s_add_i32 s1, s0, s21
	s_mov_b32 m0, s1
	s_add_i32 s0, s0, s14
	global_load_lds_dwordx4 v[236:237], off
	s_add_i32 m0, s1, 0x4000
	s_nop 0
	global_load_lds_dwordx4 v[238:239], off
	s_mov_b32 m0, s0
	s_nop 0
	global_load_lds_dwordx4 v[240:241], off
	s_add_i32 m0, s0, 0x4000
	s_nop 0
	global_load_lds_dwordx4 v[242:243], off
